# all twelve E1/E2/E3 row all-reduce butterflies (incl. register-renamed ones) converted in place to DPP + permlane swaps, on top of v062
# baseline (speedup 1.0000x reference)
; __device__ __forceinline__ unsigned pk2(float lo, float hi) { const f32x2_pk v = {lo, hi}; return __builtin_bit_cast(unsigned, __builtin_convertvector(v, bf16x2_pk)); }
; __device__ __forceinline__ float bflo(unsigned w) { return __uint_as_float(w << 16); }
; __device__ __forceinline__ float bfhi(unsigned w) { return __uint_as_float(w & 0xffff0000u); }
; #define RS ((float*)(WSP() + WS_RS))
; template <bool HAS_G, bool HAS_PRE, bool HAS_F, bool HAS_P, bool HIN32, bool HOUT32> ...
;     ...
;         for (int j = 0; j < 4; ++j) { if (HIN32) v[j] = h32[u][j]; else v[j] = (f32x4){bflo(hbr[u][j].x), bfhi(hbr[u][j].x), bflo(hbr[u][j].y), bfhi(hbr[u][j].y)};
;             if (HAS_G) g[j] = (f32x4){bflo(gbr[u][j].x), bfhi(gbr[u][j].x), bflo(gbr[u][j].y), bfhi(gbr[u][j].y)}; }
;         if (m + 2 * NGW < M) E_LOAD(u, m + 2 * NGW);
;         if (HAS_G) {
;             float ss = 0.f;
; #pragma unroll
;             for (int j = 0; j < 4; ++j) ss += (g[j][0] * g[j][0] + g[j][1] * g[j][1]) + (g[j][2] * g[j][2] + g[j][3] * g[j][3]);
;             const float r = __builtin_amdgcn_rsqf(wave_sum(ss) * (1.f / DM) + EPS)    ;
; #pragma unroll
;             for (int j = 0; j < 4; ++j) { v[j] = v[j] + g[j] * r * gp[j];
;                 if (HOUT32) __builtin_nontemporal_store(v[j], (f32x4*)((float*)hout_ + mm * DM + 4 * lane + 256 * j));
;                 else { v2u w; w.x = pk2(v[j][0], v[j][1]); w.y = pk2(v[j][2], v[j][3]); *(v2u*)((bf16*)hout_ + mm * DM + 4 * lane + 256 * j) = w; } }
;         }
;         if (!HAS_G && hout_) {
; #pragma unroll
;             for (int j = 0; j < 4; ++j) { v2u w; w.x = pk2(v[j][0], v[j][1]); w.y = pk2(v[j][2], v[j][3]); *(v2u*)((bf16*)hout_ + mm * DM + 4 * lane + 256 * j) = w; } }
;         if (HAS_PRE) {
;             float ss = 0.f;
; #pragma unroll
;             for (int j = 0; j < 4; ++j) ss += (v[j][0] * v[j][0] + v[j][1] * v[j][1]) + (v[j][2] * v[j][2] + v[j][3] * v[j][3]);
;             const float r = __builtin_amdgcn_rsqf(wave_sum(ss) * (1.f / DM) + EPS)    ;
;             if (lane == 0) RS[mm] = r;
.LBB0_604:
	v_lshlrev_b32_e32 v79, 16, v71
	v_lshlrev_b32_e32 v78, 16, v70
	v_and_b32_e32 v71, 0xffff0000, v71
	v_and_b32_e32 v70, 0xffff0000, v70
	v_pk_mul_f32 v[86:87], v[70:71], v[70:71]
	v_lshlrev_b32_e32 v81, 16, v67
	v_lshlrev_b32_e32 v80, 16, v66
	v_and_b32_e32 v67, 0xffff0000, v67
	v_and_b32_e32 v66, 0xffff0000, v66
	v_pk_fma_f32 v[86:87], v[78:79], v[78:79], v[86:87]
	v_lshlrev_b32_e32 v82, 16, v64
	v_and_b32_e32 v83, 0xffff0000, v64
	v_lshlrev_b32_e32 v64, 16, v65
	v_lshlrev_b32_e32 v84, 16, v60
	v_pk_add_f32 v[86:87], v[86:87], v[86:87] op_sel_hi:[0,1]
	v_pk_mul_f32 v[88:89], v[66:67], v[66:67]
	v_and_b32_e32 v65, 0xffff0000, v65
	v_pk_fma_f32 v[88:89], v[80:81], v[80:81], v[88:89]
	v_mul_f32_e32 v85, v82, v82
	v_mul_f32_e32 v91, v83, v83
	v_mul_f32_e32 v86, v64, v64
	v_mov_b32_e32 v90, v84
	v_and_b32_e32 v98, 0xffff0000, v60
	v_lshlrev_b32_e32 v60, 16, v61
	v_and_b32_e32 v61, 0xffff0000, v61
	v_pk_add_f32 v[88:89], v[88:89], v[88:89] op_sel_hi:[0,1]
	v_pk_fma_f32 v[92:93], v[64:65], v[64:65], v[86:87] op_sel_hi:[1,1,0]
	v_pk_add_f32 v[90:91], v[84:85], v[90:91]
	v_mul_f32_e32 v92, v98, v98
	v_mul_f32_e32 v88, v60, v60
	v_mul_f32_e32 v86, v61, v61
	v_mul_f32_e32 v94, v84, v84
	v_mov_b32_e32 v95, v91
	v_pk_add_f32 v[90:91], v[94:95], v[92:93]
	v_pk_add_f32 v[86:87], v[88:89], v[86:87]
	v_mov_b32_e32 v96, v78
	v_pk_add_f32 v[86:87], v[90:91], v[86:87]
	v_mov_b32_e32 v97, v70
	v_add_f32_e32 v85, v86, v87
	s_waitcnt lgkmcnt(0)
	s_nop 1
	v_add_f32_dpp v85, v85, v85 quad_perm:[1,0,3,2] row_mask:0xf bank_mask:0xf
	s_nop 1
	v_add_f32_dpp v85, v85, v85 quad_perm:[2,3,0,1] row_mask:0xf bank_mask:0xf
	s_nop 1
	v_add_f32_dpp v85, v85, v85 row_half_mirror row_mask:0xf bank_mask:0xf
	s_nop 1
	v_add_f32_dpp v85, v85, v85 row_mirror row_mask:0xf bank_mask:0xf
	v_mov_b32_e32 v86, v85
	s_nop 1
	v_permlane16_swap_b32_e32 v85, v86
	v_add_f32_e32 v85, v85, v86
	v_mov_b32_e32 v86, v85
	s_nop 1
	v_permlane32_swap_b32_e32 v85, v86
	v_add_f32_e32 v85, v85, v86
	v_mov_b32_e32 v70, v79
	v_and_b32_e32 v87, 0xffff0000, v68
	v_and_b32_e32 v93, 0xffff0000, v56
	v_mov_b32_e32 v78, v80
	v_mov_b32_e32 v79, v66
	v_mov_b32_e32 v66, v81
	v_and_b32_e32 v89, 0xffff0000, v62
	v_and_b32_e32 v91, 0xffff0000, v58
	v_lshlrev_b32_e32 v86, 16, v68
	v_lshlrev_b32_e32 v68, 16, v69
	v_and_b32_e32 v69, 0xffff0000, v69
	s_mov_b32 s7, 0x6800000
	v_lshlrev_b32_e32 v88, 16, v62
	v_lshlrev_b32_e32 v62, 16, v63
	v_and_b32_e32 v63, 0xffff0000, v63
	v_lshlrev_b32_e32 v90, 16, v58
	v_lshlrev_b32_e32 v58, 16, v59
	v_and_b32_e32 v59, 0xffff0000, v59
	v_lshlrev_b32_e32 v92, 16, v56
	v_lshlrev_b32_e32 v56, 16, v57
	v_and_b32_e32 v57, 0xffff0000, v57
	v_fmamk_f32 v85, v85, 0x3a800000, v214
	v_rsq_f32_e32 v94, v85
	v_mov_b32_e32 v85, v98
	v_pk_mul_f32 v[96:97], v[94:95], v[96:97] op_sel_hi:[0,1]
	v_pk_mul_f32 v[70:71], v[94:95], v[70:71] op_sel_hi:[0,1]
	v_pk_fma_f32 v[68:69], v[4:5], v[70:71], v[68:69]
	v_pk_fma_f32 v[70:71], v[2:3], v[96:97], v[86:87]
	v_pk_mul_f32 v[60:61], v[60:61], v[94:95] op_sel_hi:[1,0]
	v_pk_mul_f32 v[78:79], v[94:95], v[78:79] op_sel_hi:[0,1]
	v_pk_mul_f32 v[66:67], v[94:95], v[66:67] op_sel_hi:[0,1]
	v_pk_fma_f32 v[60:61], v[16:17], v[60:61], v[56:57]
	v_mul_f32_e32 v56, v71, v71
	v_mul_f32_e32 v57, v69, v69
	v_pk_fma_f32 v[62:63], v[8:9], v[66:67], v[62:63]
	v_pk_fma_f32 v[66:67], v[6:7], v[78:79], v[88:89]
	v_fmac_f32_e32 v56, v70, v70
	v_fmac_f32_e32 v57, v68, v68
	v_add_f32_e32 v56, v56, v57
	v_mul_f32_e32 v57, v67, v67
	v_mul_f32_e32 v80, v63, v63
	v_pk_mul_f32 v[78:79], v[82:83], v[94:95] op_sel_hi:[1,0]
	v_pk_mul_f32 v[64:65], v[64:65], v[94:95] op_sel_hi:[1,0]
	v_fmac_f32_e32 v57, v66, v66
	v_fmac_f32_e32 v80, v62, v62
	v_pk_fma_f32 v[58:59], v[12:13], v[64:65], v[58:59]
	v_pk_fma_f32 v[64:65], v[10:11], v[78:79], v[90:91]
	v_add_f32_e32 v57, v57, v80
	v_add_f32_e32 v56, v56, v57
	v_mul_f32_e32 v57, v65, v65
	v_mul_f32_e32 v80, v59, v59
	v_pk_mul_f32 v[78:79], v[84:85], v[94:95] op_sel_hi:[1,0]
	v_fmac_f32_e32 v57, v64, v64
	v_fmac_f32_e32 v80, v58, v58
	v_pk_fma_f32 v[78:79], v[14:15], v[78:79], v[92:93]
	v_add_f32_e32 v57, v57, v80
	v_add_f32_e32 v56, v57, v56
	v_mul_f32_e32 v57, v79, v79
	v_mul_f32_e32 v80, v61, v61
	v_fmac_f32_e32 v57, v78, v78
	v_fmac_f32_e32 v80, v60, v60
	v_add_f32_e32 v57, v57, v80
	v_add_f32_e32 v56, v57, v56
	s_waitcnt lgkmcnt(0)
	s_nop 1
	v_add_f32_dpp v56, v56, v56 quad_perm:[1,0,3,2] row_mask:0xf bank_mask:0xf
	s_nop 1
	v_add_f32_dpp v56, v56, v56 quad_perm:[2,3,0,1] row_mask:0xf bank_mask:0xf
	s_nop 1
	v_add_f32_dpp v56, v56, v56 row_half_mirror row_mask:0xf bank_mask:0xf
	s_nop 1
	v_add_f32_dpp v56, v56, v56 row_mirror row_mask:0xf bank_mask:0xf
	v_mov_b32_e32 v57, v56
	s_nop 1
	v_permlane16_swap_b32_e32 v56, v57
	v_add_f32_e32 v56, v56, v57
	v_mov_b32_e32 v57, v56
	s_nop 1
	v_permlane32_swap_b32_e32 v56, v57
	v_add_f32_e32 v56, v56, v57
	v_cvt_pk_bf16_f32 v70, v70, v71
	v_cvt_pk_bf16_f32 v71, v68, v69
	v_mov_b32_e32 v80, v56
	v_lshl_add_u64 v[56:57], s[18:19], 0, v[0:1]
	v_add_co_u32_e32 v68, vcc, s7, v56
	v_cvt_pk_bf16_f32 v56, v66, v67
	v_addc_co_u32_e32 v69, vcc, 0, v57, vcc
	v_cvt_pk_bf16_f32 v57, v62, v63
	global_store_dwordx2 v[68:69], v[56:57], off offset:512
	v_mov_b32_e32 v66, v80
	v_cvt_pk_bf16_f32 v62, v64, v65
	v_cvt_pk_bf16_f32 v63, v58, v59
	v_cvt_pk_bf16_f32 v58, v78, v79
	v_cvt_pk_bf16_f32 v59, v60, v61
	v_mov_b32_e32 v56, v66
	global_store_dwordx2 v[68:69], v[70:71], off
	global_store_dwordx2 v[68:69], v[62:63], off offset:1024
	global_store_dwordx2 v[68:69], v[58:59], off offset:1536
	s_and_saveexec_b64 s[20:21], s[4:5]
	s_cbranch_execz .LBB0_606
	v_fmamk_f32 v56, v56, 0x3a800000, v214
	v_rsq_f32_e32 v56, v56
	global_store_dword v1, v56, s[14:15]

; __device__ __forceinline__ unsigned pk2(float lo, float hi) { const f32x2_pk v = {lo, hi}; return __builtin_bit_cast(unsigned, __builtin_convertvector(v, bf16x2_pk)); }
; __device__ __forceinline__ float bflo(unsigned w) { return __uint_as_float(w << 16); }
; __device__ __forceinline__ float bfhi(unsigned w) { return __uint_as_float(w & 0xffff0000u); }
; #define RS ((float*)(WSP() + WS_RS))
; template <bool HAS_G, bool HAS_PRE, bool HAS_F, bool HAS_P, bool HIN32, bool HOUT32> ...
;     ...
;         for (int j = 0; j < 4; ++j) { if (HIN32) v[j] = h32[u][j]; else v[j] = (f32x4){bflo(hbr[u][j].x), bfhi(hbr[u][j].x), bflo(hbr[u][j].y), bfhi(hbr[u][j].y)};
;             if (HAS_G) g[j] = (f32x4){bflo(gbr[u][j].x), bfhi(gbr[u][j].x), bflo(gbr[u][j].y), bfhi(gbr[u][j].y)}; }
;         if (m + 2 * NGW < M) E_LOAD(u, m + 2 * NGW);
;         if (HAS_G) {
;             float ss = 0.f;
; #pragma unroll
;             for (int j = 0; j < 4; ++j) ss += (g[j][0] * g[j][0] + g[j][1] * g[j][1]) + (g[j][2] * g[j][2] + g[j][3] * g[j][3]);
;             const float r = __builtin_amdgcn_rsqf(wave_sum(ss) * (1.f / DM) + EPS)    ;
; #pragma unroll
;             for (int j = 0; j < 4; ++j) { v[j] = v[j] + g[j] * r * gp[j];
;                 if (HOUT32) __builtin_nontemporal_store(v[j], (f32x4*)((float*)hout_ + mm * DM + 4 * lane + 256 * j));
;                 else { v2u w; w.x = pk2(v[j][0], v[j][1]); w.y = pk2(v[j][2], v[j][3]); *(v2u*)((bf16*)hout_ + mm * DM + 4 * lane + 256 * j) = w; } }
;         }
;         if (!HAS_G && hout_) {
; #pragma unroll
;             for (int j = 0; j < 4; ++j) { v2u w; w.x = pk2(v[j][0], v[j][1]); w.y = pk2(v[j][2], v[j][3]); *(v2u*)((bf16*)hout_ + mm * DM + 4 * lane + 256 * j) = w; } }
;         if (HAS_PRE) {
;             float ss = 0.f;
; #pragma unroll
;             for (int j = 0; j < 4; ++j) ss += (v[j][0] * v[j][0] + v[j][1] * v[j][1]) + (v[j][2] * v[j][2] + v[j][3] * v[j][3]);
;             const float r = __builtin_amdgcn_rsqf(wave_sum(ss) * (1.f / DM) + EPS)    ;
;             if (lane == 0) RS[mm] = r;
.LBB0_608:
	v_lshlrev_b32_e32 v79, 16, v55
	v_lshlrev_b32_e32 v78, 16, v54
	v_and_b32_e32 v55, 0xffff0000, v55
	v_and_b32_e32 v54, 0xffff0000, v54
	v_pk_mul_f32 v[86:87], v[54:55], v[54:55]
	v_lshlrev_b32_e32 v81, 16, v53
	v_lshlrev_b32_e32 v80, 16, v52
	v_and_b32_e32 v53, 0xffff0000, v53
	v_and_b32_e32 v52, 0xffff0000, v52
	v_pk_fma_f32 v[86:87], v[78:79], v[78:79], v[86:87]
	v_lshlrev_b32_e32 v82, 16, v50
	v_and_b32_e32 v83, 0xffff0000, v50
	v_lshlrev_b32_e32 v50, 16, v51
	v_lshlrev_b32_e32 v84, 16, v48
	v_pk_add_f32 v[86:87], v[86:87], v[86:87] op_sel_hi:[0,1]
	v_pk_mul_f32 v[88:89], v[52:53], v[52:53]
	v_and_b32_e32 v51, 0xffff0000, v51
	v_pk_fma_f32 v[88:89], v[80:81], v[80:81], v[88:89]
	v_mul_f32_e32 v85, v82, v82
	v_mul_f32_e32 v91, v83, v83
	v_mul_f32_e32 v86, v50, v50
	v_mov_b32_e32 v90, v84
	v_and_b32_e32 v98, 0xffff0000, v48
	v_lshlrev_b32_e32 v48, 16, v49
	v_and_b32_e32 v49, 0xffff0000, v49
	v_pk_add_f32 v[88:89], v[88:89], v[88:89] op_sel_hi:[0,1]
	v_pk_fma_f32 v[92:93], v[50:51], v[50:51], v[86:87] op_sel_hi:[1,1,0]
	v_pk_add_f32 v[90:91], v[84:85], v[90:91]
	v_mul_f32_e32 v92, v98, v98
	v_mul_f32_e32 v88, v48, v48
	v_mul_f32_e32 v86, v49, v49
	v_mul_f32_e32 v94, v84, v84
	v_mov_b32_e32 v95, v91
	v_pk_add_f32 v[90:91], v[94:95], v[92:93]
	v_pk_add_f32 v[86:87], v[88:89], v[86:87]
	v_mov_b32_e32 v96, v78
	v_pk_add_f32 v[86:87], v[90:91], v[86:87]
	v_mov_b32_e32 v97, v54
	v_add_f32_e32 v85, v86, v87
	s_waitcnt lgkmcnt(0)
	s_nop 1
	v_add_f32_dpp v85, v85, v85 quad_perm:[1,0,3,2] row_mask:0xf bank_mask:0xf
	s_nop 1
	v_add_f32_dpp v85, v85, v85 quad_perm:[2,3,0,1] row_mask:0xf bank_mask:0xf
	s_nop 1
	v_add_f32_dpp v85, v85, v85 row_half_mirror row_mask:0xf bank_mask:0xf
	s_nop 1
	v_add_f32_dpp v85, v85, v85 row_mirror row_mask:0xf bank_mask:0xf
	v_mov_b32_e32 v86, v85
	s_nop 1
	v_permlane16_swap_b32_e32 v85, v86
	v_add_f32_e32 v85, v85, v86
	v_mov_b32_e32 v86, v85
	s_nop 1
	v_permlane32_swap_b32_e32 v85, v86
	v_add_f32_e32 v85, v85, v86
	v_mov_b32_e32 v54, v79
	v_and_b32_e32 v87, 0xffff0000, v46
	v_and_b32_e32 v93, 0xffff0000, v40
	v_mov_b32_e32 v78, v80
	v_mov_b32_e32 v79, v52
	v_mov_b32_e32 v52, v81
	v_and_b32_e32 v89, 0xffff0000, v44
	v_and_b32_e32 v91, 0xffff0000, v42
	v_lshlrev_b32_e32 v86, 16, v46
	v_lshlrev_b32_e32 v46, 16, v47
	v_and_b32_e32 v47, 0xffff0000, v47
	s_add_i32 s20, s28, s2
	v_lshlrev_b32_e32 v88, 16, v44
	v_lshlrev_b32_e32 v44, 16, v45
	v_and_b32_e32 v45, 0xffff0000, v45
	s_ashr_i32 s21, s20, 31
	v_lshlrev_b32_e32 v90, 16, v42
	v_lshlrev_b32_e32 v42, 16, v43
	v_and_b32_e32 v43, 0xffff0000, v43
	s_lshl_b64 s[22:23], s[20:21], 11
	v_lshlrev_b32_e32 v92, 16, v40
	v_lshlrev_b32_e32 v40, 16, v41
	v_and_b32_e32 v41, 0xffff0000, v41
	v_fmamk_f32 v85, v85, 0x3a800000, v214
	v_rsq_f32_e32 v94, v85
	v_mov_b32_e32 v85, v98
	v_pk_mul_f32 v[96:97], v[94:95], v[96:97] op_sel_hi:[0,1]
	v_pk_mul_f32 v[54:55], v[94:95], v[54:55] op_sel_hi:[0,1]
	v_pk_fma_f32 v[46:47], v[4:5], v[54:55], v[46:47]
	v_pk_fma_f32 v[54:55], v[2:3], v[96:97], v[86:87]
	v_pk_mul_f32 v[48:49], v[48:49], v[94:95] op_sel_hi:[1,0]
	v_pk_mul_f32 v[78:79], v[94:95], v[78:79] op_sel_hi:[0,1]
	v_pk_mul_f32 v[52:53], v[94:95], v[52:53] op_sel_hi:[0,1]
	v_pk_fma_f32 v[48:49], v[16:17], v[48:49], v[40:41]
	v_mul_f32_e32 v40, v55, v55
	v_mul_f32_e32 v41, v47, v47
	v_pk_fma_f32 v[44:45], v[8:9], v[52:53], v[44:45]
	v_pk_fma_f32 v[52:53], v[6:7], v[78:79], v[88:89]
	v_fmac_f32_e32 v40, v54, v54
	v_fmac_f32_e32 v41, v46, v46
	v_add_f32_e32 v40, v40, v41
	v_mul_f32_e32 v41, v53, v53
	v_mul_f32_e32 v80, v45, v45
	v_pk_mul_f32 v[78:79], v[82:83], v[94:95] op_sel_hi:[1,0]
	v_pk_mul_f32 v[50:51], v[50:51], v[94:95] op_sel_hi:[1,0]
	v_fmac_f32_e32 v41, v52, v52
	v_fmac_f32_e32 v80, v44, v44
	v_pk_fma_f32 v[42:43], v[12:13], v[50:51], v[42:43]
	v_pk_fma_f32 v[50:51], v[10:11], v[78:79], v[90:91]
	v_add_f32_e32 v41, v41, v80
	v_add_f32_e32 v40, v40, v41
	v_mul_f32_e32 v41, v51, v51
	v_mul_f32_e32 v80, v43, v43
	v_pk_mul_f32 v[78:79], v[84:85], v[94:95] op_sel_hi:[1,0]
	v_fmac_f32_e32 v41, v50, v50
	v_fmac_f32_e32 v80, v42, v42
	v_pk_fma_f32 v[78:79], v[14:15], v[78:79], v[92:93]
	v_add_f32_e32 v41, v41, v80
	v_add_f32_e32 v40, v41, v40
	v_mul_f32_e32 v41, v79, v79
	v_mul_f32_e32 v80, v49, v49
	v_fmac_f32_e32 v41, v78, v78
	v_fmac_f32_e32 v80, v48, v48
	v_add_f32_e32 v41, v41, v80
	v_add_f32_e32 v40, v41, v40
	s_waitcnt lgkmcnt(0)
	s_nop 1
	v_add_f32_dpp v40, v40, v40 quad_perm:[1,0,3,2] row_mask:0xf bank_mask:0xf
	s_nop 1
	v_add_f32_dpp v40, v40, v40 quad_perm:[2,3,0,1] row_mask:0xf bank_mask:0xf
	s_nop 1
	v_add_f32_dpp v40, v40, v40 row_half_mirror row_mask:0xf bank_mask:0xf
	s_nop 1
	v_add_f32_dpp v40, v40, v40 row_mirror row_mask:0xf bank_mask:0xf
	v_mov_b32_e32 v41, v40
	s_nop 1
	v_permlane16_swap_b32_e32 v40, v41
	v_add_f32_e32 v40, v40, v41
	v_mov_b32_e32 v41, v40
	s_nop 1
	v_permlane32_swap_b32_e32 v40, v41
	v_add_f32_e32 v40, v40, v41
	v_lshl_add_u64 v[80:81], v[18:19], 0, s[22:23]
	v_mov_b32_e32 v82, v40
	v_cvt_pk_bf16_f32 v41, v46, v47
	v_cvt_pk_bf16_f32 v40, v54, v55
	global_store_dwordx2 v[80:81], v[40:41], off
	v_cvt_pk_bf16_f32 v40, v52, v53
	v_mov_b32_e32 v46, v82
	v_cvt_pk_bf16_f32 v41, v44, v45
	global_store_dwordx2 v[80:81], v[40:41], off offset:512
	v_cvt_pk_bf16_f32 v44, v50, v51
	v_cvt_pk_bf16_f32 v45, v42, v43
	v_mov_b32_e32 v40, v46
	v_cvt_pk_bf16_f32 v42, v78, v79
	v_cvt_pk_bf16_f32 v43, v48, v49
	global_store_dwordx2 v[80:81], v[44:45], off offset:1024
	global_store_dwordx2 v[80:81], v[42:43], off offset:1536
	s_and_saveexec_b64 s[22:23], s[4:5]
	s_cbranch_execz .LBB0_601
	v_fmamk_f32 v40, v40, 0x3a800000, v214
	v_rsq_f32_e32 v40, v40
	s_lshl_b64 s[20:21], s[20:21], 2
	s_add_u32 s20, s25, s20
	s_addc_u32 s21, s26, s21
	global_store_dword v1, v40, s[20:21]
	s_branch .LBB0_601

; __device__ __forceinline__ unsigned pk2(float lo, float hi) { const f32x2_pk v = {lo, hi}; return __builtin_bit_cast(unsigned, __builtin_convertvector(v, bf16x2_pk)); }
; __device__ __forceinline__ float bflo(unsigned w) { return __uint_as_float(w << 16); }
; __device__ __forceinline__ float bfhi(unsigned w) { return __uint_as_float(w & 0xffff0000u); }
; #define RS ((float*)(WSP() + WS_RS))
; template <bool HAS_G, bool HAS_PRE, bool HAS_F, bool HAS_P, bool HIN32, bool HOUT32> ...
;     ...
;         for (int j = 0; j < 4; ++j) { if (HIN32) v[j] = h32[u][j]; else v[j] = (f32x4){bflo(hbr[u][j].x), bfhi(hbr[u][j].x), bflo(hbr[u][j].y), bfhi(hbr[u][j].y)};
;             if (HAS_G) g[j] = (f32x4){bflo(gbr[u][j].x), bfhi(gbr[u][j].x), bflo(gbr[u][j].y), bfhi(gbr[u][j].y)}; }
;         if (m + 2 * NGW < M) E_LOAD(u, m + 2 * NGW);
;         if (HAS_G) {
;             float ss = 0.f;
; #pragma unroll
;             for (int j = 0; j < 4; ++j) ss += (g[j][0] * g[j][0] + g[j][1] * g[j][1]) + (g[j][2] * g[j][2] + g[j][3] * g[j][3]);
;             const float r = __builtin_amdgcn_rsqf(wave_sum(ss) * (1.f / DM) + EPS)    ;
; #pragma unroll
;             for (int j = 0; j < 4; ++j) { v[j] = v[j] + g[j] * r * gp[j];
;                 if (HOUT32) __builtin_nontemporal_store(v[j], (f32x4*)((float*)hout_ + mm * DM + 4 * lane + 256 * j));
;                 else { v2u w; w.x = pk2(v[j][0], v[j][1]); w.y = pk2(v[j][2], v[j][3]); *(v2u*)((bf16*)hout_ + mm * DM + 4 * lane + 256 * j) = w; } }
;         }
;         if (!HAS_G && hout_) {
; #pragma unroll
;             for (int j = 0; j < 4; ++j) { v2u w; w.x = pk2(v[j][0], v[j][1]); w.y = pk2(v[j][2], v[j][3]); *(v2u*)((bf16*)hout_ + mm * DM + 4 * lane + 256 * j) = w; } }
;         if (HAS_PRE) {
;             float ss = 0.f;
; #pragma unroll
;             for (int j = 0; j < 4; ++j) ss += (v[j][0] * v[j][0] + v[j][1] * v[j][1]) + (v[j][2] * v[j][2] + v[j][3] * v[j][3]);
;             const float r = __builtin_amdgcn_rsqf(wave_sum(ss) * (1.f / DM) + EPS)    ;
;             if (lane == 0) RS[mm] = r;
.LBB0_987:
	v_lshlrev_b32_e32 v167, 16, v157
	v_lshlrev_b32_e32 v166, 16, v156
	v_and_b32_e32 v157, 0xffff0000, v157
	v_and_b32_e32 v156, 0xffff0000, v156
	v_lshlrev_b32_e32 v169, 16, v153
	v_lshlrev_b32_e32 v168, 16, v152
	v_and_b32_e32 v171, 0xffff0000, v153
	v_and_b32_e32 v170, 0xffff0000, v152
	v_pk_mul_f32 v[152:153], v[156:157], v[156:157]
	v_lshlrev_b32_e32 v172, 16, v150
	v_pk_fma_f32 v[152:153], v[166:167], v[166:167], v[152:153]
	v_and_b32_e32 v173, 0xffff0000, v150
	v_lshlrev_b32_e32 v150, 16, v151
	v_lshlrev_b32_e32 v174, 16, v146
	v_pk_add_f32 v[152:153], v[152:153], v[152:153] op_sel_hi:[0,1]
	v_pk_mul_f32 v[176:177], v[170:171], v[170:171]
	v_and_b32_e32 v151, 0xffff0000, v151
	v_pk_fma_f32 v[176:177], v[168:169], v[168:169], v[176:177]
	v_mul_f32_e32 v175, v172, v172
	v_mul_f32_e32 v179, v173, v173
	v_mul_f32_e32 v152, v150, v150
	v_mov_b32_e32 v178, v174
	v_and_b32_e32 v165, 0xffff0000, v146
	v_lshlrev_b32_e32 v146, 16, v147
	v_and_b32_e32 v147, 0xffff0000, v147
	v_pk_add_f32 v[176:177], v[176:177], v[176:177] op_sel_hi:[0,1]
	v_pk_fma_f32 v[180:181], v[150:151], v[150:151], v[152:153] op_sel_hi:[1,1,0]
	v_pk_add_f32 v[178:179], v[174:175], v[178:179]
	v_mul_f32_e32 v180, v165, v165
	v_mul_f32_e32 v176, v146, v146
	v_mul_f32_e32 v152, v147, v147
	v_mul_f32_e32 v182, v174, v174
	v_mov_b32_e32 v183, v179
	v_pk_add_f32 v[178:179], v[182:183], v[180:181]
	v_pk_add_f32 v[152:153], v[176:177], v[152:153]
	v_mov_b32_e32 v184, v166
	v_pk_add_f32 v[152:153], v[178:179], v[152:153]
	v_mov_b32_e32 v185, v156
	v_add_f32_e32 v152, v152, v153
	s_waitcnt lgkmcnt(0)
	s_nop 1
	v_add_f32_dpp v152, v152, v152 quad_perm:[1,0,3,2] row_mask:0xf bank_mask:0xf
	s_nop 1
	v_add_f32_dpp v152, v152, v152 quad_perm:[2,3,0,1] row_mask:0xf bank_mask:0xf
	s_nop 1
	v_add_f32_dpp v152, v152, v152 row_half_mirror row_mask:0xf bank_mask:0xf
	s_nop 1
	v_add_f32_dpp v152, v152, v152 row_mirror row_mask:0xf bank_mask:0xf
	v_mov_b32_e32 v153, v152
	s_nop 1
	v_permlane16_swap_b32_e32 v152, v153
	v_add_f32_e32 v152, v152, v153
	v_mov_b32_e32 v153, v152
	s_nop 1
	v_permlane32_swap_b32_e32 v152, v153
	v_add_f32_e32 v152, v152, v153
	v_mov_b32_e32 v156, v167
	v_mov_b32_e32 v166, v168
	v_mov_b32_e32 v167, v170
	v_lshlrev_b32_e32 v176, 16, v154
	v_and_b32_e32 v177, 0xffff0000, v154
	v_lshlrev_b32_e32 v154, 16, v148
	v_and_b32_e32 v179, 0xffff0000, v144
	v_and_b32_e32 v181, 0xffff0000, v142
	v_mov_b32_e32 v153, v152
	v_lshlrev_b32_e32 v152, 16, v155
	v_mov_b32_e32 v170, v169
	s_mov_b32 s15, 0x6800000
	v_mov_b32_e32 v175, v153
	v_and_b32_e32 v153, 0xffff0000, v155
	v_and_b32_e32 v155, 0xffff0000, v148
	v_lshlrev_b32_e32 v148, 16, v149
	v_and_b32_e32 v149, 0xffff0000, v149
	v_lshlrev_b32_e32 v178, 16, v144
	v_lshlrev_b32_e32 v144, 16, v145
	v_and_b32_e32 v145, 0xffff0000, v145
	v_lshlrev_b32_e32 v180, 16, v142
	v_lshlrev_b32_e32 v142, 16, v143
	v_and_b32_e32 v143, 0xffff0000, v143
	v_fmamk_f32 v175, v175, 0x3a800000, v214
	v_rsq_f32_e32 v182, v175
	v_mov_b32_e32 v175, v165
	v_pk_mul_f32 v[166:167], v[182:183], v[166:167] op_sel_hi:[0,1]
	v_pk_mul_f32 v[184:185], v[182:183], v[184:185] op_sel_hi:[0,1]
	v_pk_mul_f32 v[156:157], v[182:183], v[156:157] op_sel_hi:[0,1]
	v_pk_fma_f32 v[154:155], v[6:7], v[166:167], v[154:155]
	v_pk_mul_f32 v[166:167], v[172:173], v[182:183] op_sel_hi:[1,0]
	v_pk_mul_f32 v[150:151], v[150:151], v[182:183] op_sel_hi:[1,0]
	v_pk_fma_f32 v[152:153], v[4:5], v[156:157], v[152:153]
	v_pk_fma_f32 v[156:157], v[2:3], v[184:185], v[176:177]
	v_pk_fma_f32 v[144:145], v[12:13], v[150:151], v[144:145]
	v_pk_fma_f32 v[150:151], v[10:11], v[166:167], v[178:179]
	v_pk_mul_f32 v[166:167], v[174:175], v[182:183] op_sel_hi:[1,0]
	v_pk_mul_f32 v[146:147], v[146:147], v[182:183] op_sel_hi:[1,0]
	v_pk_mul_f32 v[168:169], v[182:183], v[170:171] op_sel_hi:[0,1]
	v_pk_fma_f32 v[142:143], v[16:17], v[146:147], v[142:143]
	v_pk_fma_f32 v[146:147], v[14:15], v[166:167], v[180:181]
	v_mul_f32_e32 v165, v157, v157
	v_mul_f32_e32 v166, v153, v153
	v_pk_fma_f32 v[148:149], v[8:9], v[168:169], v[148:149]
	v_fmac_f32_e32 v165, v156, v156
	v_fmac_f32_e32 v166, v152, v152
	v_add_f32_e32 v165, v165, v166
	v_mul_f32_e32 v166, v155, v155
	v_mul_f32_e32 v167, v149, v149
	v_fmac_f32_e32 v166, v154, v154
	v_fmac_f32_e32 v167, v148, v148
	v_add_f32_e32 v166, v166, v167
	v_add_f32_e32 v165, v165, v166
	v_mul_f32_e32 v166, v151, v151
	v_mul_f32_e32 v167, v145, v145
	v_fmac_f32_e32 v166, v150, v150
	v_fmac_f32_e32 v167, v144, v144
	v_add_f32_e32 v166, v166, v167
	v_add_f32_e32 v165, v166, v165
	v_mul_f32_e32 v166, v147, v147
	v_mul_f32_e32 v167, v143, v143
	v_fmac_f32_e32 v166, v146, v146
	v_fmac_f32_e32 v167, v142, v142
	v_add_f32_e32 v166, v166, v167
	v_add_f32_e32 v165, v166, v165
	s_waitcnt lgkmcnt(0)
	s_nop 1
	v_add_f32_dpp v165, v165, v165 quad_perm:[1,0,3,2] row_mask:0xf bank_mask:0xf
	s_nop 1
	v_add_f32_dpp v165, v165, v165 quad_perm:[2,3,0,1] row_mask:0xf bank_mask:0xf
	s_nop 1
	v_add_f32_dpp v165, v165, v165 row_half_mirror row_mask:0xf bank_mask:0xf
	s_nop 1
	v_add_f32_dpp v165, v165, v165 row_mirror row_mask:0xf bank_mask:0xf
	v_mov_b32_e32 v166, v165
	s_nop 1
	v_permlane16_swap_b32_e32 v165, v166
	v_add_f32_e32 v165, v165, v166
	v_mov_b32_e32 v166, v165
	s_nop 1
	v_permlane32_swap_b32_e32 v165, v166
	v_add_f32_e32 v165, v165, v166
	v_cvt_pk_bf16_f32 v168, v156, v157
	v_cvt_pk_bf16_f32 v169, v152, v153
	v_lshl_add_u64 v[166:167], s[28:29], 0, v[0:1]
	v_add_co_u32_e32 v166, vcc, s15, v166
	v_addc_co_u32_e32 v167, vcc, 0, v167, vcc
	global_store_dwordx2 v[166:167], v[168:169], off
	v_cvt_pk_bf16_f32 v168, v154, v155
	v_cvt_pk_bf16_f32 v169, v148, v149
	global_store_dwordx2 v[166:167], v[168:169], off offset:512
	v_cvt_pk_bf16_f32 v168, v150, v151
	v_cvt_pk_bf16_f32 v169, v144, v145
	v_fmamk_f32 v165, v165, 0x3a800000, v214
	v_rsq_f32_e32 v165, v165
	global_store_dwordx2 v[166:167], v[168:169], off offset:1024
	v_cvt_pk_bf16_f32 v168, v146, v147
	v_cvt_pk_bf16_f32 v169, v142, v143
	global_store_dwordx2 v[166:167], v[168:169], off offset:1536
	s_and_saveexec_b64 s[30:31], s[4:5]
	s_cbranch_execz .LBB0_989
	global_store_dword v1, v165, s[22:23]

; __device__ __forceinline__ unsigned pk2(float lo, float hi) { const f32x2_pk v = {lo, hi}; return __builtin_bit_cast(unsigned, __builtin_convertvector(v, bf16x2_pk)); }
; __device__ __forceinline__ float bflo(unsigned w) { return __uint_as_float(w << 16); }
; __device__ __forceinline__ float bfhi(unsigned w) { return __uint_as_float(w & 0xffff0000u); }
; #define RS ((float*)(WSP() + WS_RS))
; template <bool HAS_G, bool HAS_PRE, bool HAS_F, bool HAS_P, bool HIN32, bool HOUT32> ...
;     ...
;         for (int j = 0; j < 4; ++j) { if (HIN32) v[j] = h32[u][j]; else v[j] = (f32x4){bflo(hbr[u][j].x), bfhi(hbr[u][j].x), bflo(hbr[u][j].y), bfhi(hbr[u][j].y)};
;             if (HAS_G) g[j] = (f32x4){bflo(gbr[u][j].x), bfhi(gbr[u][j].x), bflo(gbr[u][j].y), bfhi(gbr[u][j].y)}; }
;         if (m + 2 * NGW < M) E_LOAD(u, m + 2 * NGW);
;         if (HAS_G) {
;             float ss = 0.f;
; #pragma unroll
;             for (int j = 0; j < 4; ++j) ss += (g[j][0] * g[j][0] + g[j][1] * g[j][1]) + (g[j][2] * g[j][2] + g[j][3] * g[j][3]);
;             const float r = __builtin_amdgcn_rsqf(wave_sum(ss) * (1.f / DM) + EPS)    ;
; #pragma unroll
;             for (int j = 0; j < 4; ++j) { v[j] = v[j] + g[j] * r * gp[j];
;                 if (HOUT32) __builtin_nontemporal_store(v[j], (f32x4*)((float*)hout_ + mm * DM + 4 * lane + 256 * j));
;                 else { v2u w; w.x = pk2(v[j][0], v[j][1]); w.y = pk2(v[j][2], v[j][3]); *(v2u*)((bf16*)hout_ + mm * DM + 4 * lane + 256 * j) = w; } }
;         }
;         if (!HAS_G && hout_) {
; #pragma unroll
;             for (int j = 0; j < 4; ++j) { v2u w; w.x = pk2(v[j][0], v[j][1]); w.y = pk2(v[j][2], v[j][3]); *(v2u*)((bf16*)hout_ + mm * DM + 4 * lane + 256 * j) = w; } }
;         if (HAS_PRE) {
;             float ss = 0.f;
; #pragma unroll
;             for (int j = 0; j < 4; ++j) ss += (v[j][0] * v[j][0] + v[j][1] * v[j][1]) + (v[j][2] * v[j][2] + v[j][3] * v[j][3]);
;             const float r = __builtin_amdgcn_rsqf(wave_sum(ss) * (1.f / DM) + EPS)    ;
;             if (lane == 0) RS[mm] = r;
.LBB0_993:
	v_lshlrev_b32_e32 v167, 16, v141
	v_lshlrev_b32_e32 v166, 16, v140
	v_and_b32_e32 v141, 0xffff0000, v141
	v_and_b32_e32 v140, 0xffff0000, v140
	v_lshlrev_b32_e32 v174, 16, v134
	v_and_b32_e32 v165, 0xffff0000, v134
	v_lshlrev_b32_e32 v176, 16, v135
	v_and_b32_e32 v177, 0xffff0000, v135
	v_pk_mul_f32 v[134:135], v[140:141], v[140:141]
	v_lshlrev_b32_e32 v169, 16, v139
	v_lshlrev_b32_e32 v168, 16, v138
	v_and_b32_e32 v139, 0xffff0000, v139
	v_and_b32_e32 v138, 0xffff0000, v138
	v_pk_fma_f32 v[134:135], v[166:167], v[166:167], v[134:135]
	v_lshlrev_b32_e32 v170, 16, v136
	v_and_b32_e32 v171, 0xffff0000, v136
	v_lshlrev_b32_e32 v172, 16, v137
	v_and_b32_e32 v173, 0xffff0000, v137
	v_pk_add_f32 v[134:135], v[134:135], v[134:135] op_sel_hi:[0,1]
	v_pk_mul_f32 v[136:137], v[138:139], v[138:139]
	v_mul_f32_e32 v175, v170, v170
	v_pk_fma_f32 v[136:137], v[168:169], v[168:169], v[136:137]
	v_mul_f32_e32 v179, v171, v171
	v_mul_f32_e32 v134, v172, v172
	v_mov_b32_e32 v178, v174
	v_pk_add_f32 v[136:137], v[136:137], v[136:137] op_sel_hi:[0,1]
	v_pk_fma_f32 v[180:181], v[172:173], v[172:173], v[134:135] op_sel_hi:[1,1,0]
	v_pk_add_f32 v[178:179], v[174:175], v[178:179]
	v_mul_f32_e32 v180, v165, v165
	v_mul_f32_e32 v136, v176, v176
	v_mul_f32_e32 v134, v177, v177
	v_mul_f32_e32 v182, v174, v174
	v_mov_b32_e32 v183, v179
	v_pk_add_f32 v[178:179], v[182:183], v[180:181]
	v_pk_add_f32 v[134:135], v[136:137], v[134:135]
	v_lshlrev_b32_e32 v182, 16, v126
	v_pk_add_f32 v[134:135], v[178:179], v[134:135]
	v_and_b32_e32 v183, 0xffff0000, v126
	v_add_f32_e32 v134, v134, v135
	s_waitcnt lgkmcnt(0)
	s_nop 1
	v_add_f32_dpp v134, v134, v134 quad_perm:[1,0,3,2] row_mask:0xf bank_mask:0xf
	s_nop 1
	v_add_f32_dpp v134, v134, v134 quad_perm:[2,3,0,1] row_mask:0xf bank_mask:0xf
	s_nop 1
	v_add_f32_dpp v134, v134, v134 row_half_mirror row_mask:0xf bank_mask:0xf
	s_nop 1
	v_add_f32_dpp v134, v134, v134 row_mirror row_mask:0xf bank_mask:0xf
	v_mov_b32_e32 v135, v134
	s_nop 1
	v_permlane16_swap_b32_e32 v134, v135
	v_add_f32_e32 v134, v134, v135
	v_mov_b32_e32 v135, v134
	s_nop 1
	v_permlane32_swap_b32_e32 v134, v135
	v_add_f32_e32 v134, v134, v135
	v_lshlrev_b32_e32 v126, 16, v127
	v_and_b32_e32 v127, 0xffff0000, v127
	v_lshlrev_b32_e32 v178, 16, v130
	v_and_b32_e32 v179, 0xffff0000, v130
	v_lshlrev_b32_e32 v130, 16, v131
	v_and_b32_e32 v131, 0xffff0000, v131
	v_mov_b32_e32 v175, v165
	v_lshlrev_b32_e32 v180, 16, v128
	v_mov_b32_e32 v136, v134
	v_lshlrev_b32_e32 v134, 16, v132
	v_and_b32_e32 v135, 0xffff0000, v132
	v_lshlrev_b32_e32 v132, 16, v133
	v_and_b32_e32 v133, 0xffff0000, v133
	v_and_b32_e32 v181, 0xffff0000, v128
	v_lshlrev_b32_e32 v128, 16, v129
	v_and_b32_e32 v129, 0xffff0000, v129
	s_add_i32 s30, s70, s13
	s_ashr_i32 s31, s30, 31
	s_lshl_b64 s[34:35], s[30:31], 11
	v_fmamk_f32 v136, v136, 0x3a800000, v214
	v_rsq_f32_e32 v184, v136
	v_mov_b32_e32 v136, v166
	v_mov_b32_e32 v137, v140
	v_mov_b32_e32 v140, v167
	v_pk_mul_f32 v[186:187], v[184:185], v[136:137] op_sel_hi:[0,1]
	v_pk_mul_f32 v[136:137], v[184:185], v[140:141] op_sel_hi:[0,1]
	v_pk_fma_f32 v[136:137], v[4:5], v[136:137], v[132:133]
	v_pk_fma_f32 v[140:141], v[2:3], v[186:187], v[134:135]
	v_mov_b32_e32 v132, v168
	v_mov_b32_e32 v133, v138
	v_mov_b32_e32 v138, v169
	v_pk_mul_f32 v[166:167], v[176:177], v[184:185] op_sel_hi:[1,0]
	v_pk_mul_f32 v[134:135], v[184:185], v[132:133] op_sel_hi:[0,1]
	v_pk_mul_f32 v[132:133], v[184:185], v[138:139] op_sel_hi:[0,1]
	v_pk_fma_f32 v[126:127], v[16:17], v[166:167], v[126:127]
	v_mul_f32_e32 v165, v141, v141
	v_mul_f32_e32 v166, v137, v137
	v_pk_fma_f32 v[132:133], v[8:9], v[132:133], v[130:131]
	v_pk_fma_f32 v[138:139], v[6:7], v[134:135], v[178:179]
	v_fmac_f32_e32 v165, v140, v140
	v_fmac_f32_e32 v166, v136, v136
	v_add_f32_e32 v165, v165, v166
	v_mul_f32_e32 v166, v139, v139
	v_mul_f32_e32 v167, v133, v133
	v_pk_mul_f32 v[130:131], v[170:171], v[184:185] op_sel_hi:[1,0]
	v_pk_mul_f32 v[134:135], v[172:173], v[184:185] op_sel_hi:[1,0]
	v_fmac_f32_e32 v166, v138, v138
	v_fmac_f32_e32 v167, v132, v132
	v_pk_fma_f32 v[128:129], v[12:13], v[134:135], v[128:129]
	v_pk_fma_f32 v[134:135], v[10:11], v[130:131], v[180:181]
	v_add_f32_e32 v166, v166, v167
	v_add_f32_e32 v165, v165, v166
	v_mul_f32_e32 v166, v135, v135
	v_mul_f32_e32 v167, v129, v129
	v_pk_mul_f32 v[130:131], v[174:175], v[184:185] op_sel_hi:[1,0]
	v_fmac_f32_e32 v166, v134, v134
	v_fmac_f32_e32 v167, v128, v128
	v_pk_fma_f32 v[130:131], v[14:15], v[130:131], v[182:183]
	v_add_f32_e32 v166, v166, v167
	v_add_f32_e32 v165, v166, v165
	v_mul_f32_e32 v166, v131, v131
	v_mul_f32_e32 v167, v127, v127
	v_fmac_f32_e32 v166, v130, v130
	v_fmac_f32_e32 v167, v126, v126
	v_add_f32_e32 v166, v166, v167
	v_add_f32_e32 v165, v166, v165
	s_waitcnt lgkmcnt(0)
	s_nop 1
	v_add_f32_dpp v165, v165, v165 quad_perm:[1,0,3,2] row_mask:0xf bank_mask:0xf
	s_nop 1
	v_add_f32_dpp v165, v165, v165 quad_perm:[2,3,0,1] row_mask:0xf bank_mask:0xf
	s_nop 1
	v_add_f32_dpp v165, v165, v165 row_half_mirror row_mask:0xf bank_mask:0xf
	s_nop 1
	v_add_f32_dpp v165, v165, v165 row_mirror row_mask:0xf bank_mask:0xf
	v_mov_b32_e32 v166, v165
	s_nop 1
	v_permlane16_swap_b32_e32 v165, v166
	v_add_f32_e32 v165, v165, v166
	v_mov_b32_e32 v166, v165
	s_nop 1
	v_permlane32_swap_b32_e32 v165, v166
	v_add_f32_e32 v165, v165, v166
	v_cvt_pk_bf16_f32 v168, v140, v141
	v_lshl_add_u64 v[166:167], v[98:99], 0, s[34:35]
	v_cvt_pk_bf16_f32 v169, v136, v137
	global_store_dwordx2 v[166:167], v[168:169], off
	v_cvt_pk_bf16_f32 v168, v138, v139
	v_cvt_pk_bf16_f32 v169, v132, v133
	global_store_dwordx2 v[166:167], v[168:169], off offset:512
	v_cvt_pk_bf16_f32 v168, v134, v135
	v_cvt_pk_bf16_f32 v169, v128, v129
	global_store_dwordx2 v[166:167], v[168:169], off offset:1024
	v_fmamk_f32 v165, v165, 0x3a800000, v214
	v_rsq_f32_e32 v165, v165
	v_cvt_pk_bf16_f32 v168, v130, v131
	v_cvt_pk_bf16_f32 v169, v126, v127
	global_store_dwordx2 v[166:167], v[168:169], off offset:1536
	s_and_saveexec_b64 s[34:35], s[4:5]
	s_cbranch_execz .LBB0_995
	s_lshl_b64 s[62:63], s[30:31], 2
	s_add_u32 s62, s48, s62
	s_addc_u32 s63, s49, s63
	global_store_dword v1, v165, s[62:63]
